# attention: common path skips the alpha<1 test (only reachable after a reference raise, which gets its own copy of the exp/pack block)
# speedup vs baseline: 1.0005x; 1.0005x over previous
; __device__ __forceinline__ float softmax_rel(f32x16& p0, f32x16& p1, bool first, float& m_reg, float& l_reg, bf16x8& pa0, bf16x8& pa1, bf16x8& pa2, bf16x8& pa3) {
;     ...
; #pragma unroll
;   for (int r = 0; r < 16; ++r) p0[r] = __builtin_amdgcn_exp2f(p0[r]);
; #pragma unroll
;   for (int r = 0; r < 16; ++r) p1[r] = __builtin_amdgcn_exp2f(p1[r]);
;   float ps = 0;
; #pragma unroll
;   for (int r = 0; r < 16; ++r) ps += p0[r];
; #pragma unroll
;   for (int r = 0; r < 16; ++r) ps += p1[r];
;   { auto rr = __builtin_amdgcn_permlane32_swap(__float_as_uint(ps), __float_as_uint(ps), false, false);
;     ps = __uint_as_float(rr[0]) + __uint_as_float(rr[1]); }
;   l_reg = l_reg * alpha + ps;
;   PK4(p0, 0, pa0); PK4(p0, 8, pa1); PK4(p1, 0, pa2); PK4(p1, 8, pa3);
.LBB0_355:
	v_exp_f32_e32 v144, v144
	v_exp_f32_e32 v145, v145
	v_exp_f32_e32 v146, v146
	v_exp_f32_e32 v147, v147
	v_exp_f32_e32 v148, v148
	v_exp_f32_e32 v194, v128
	v_add_f32_e32 v128, 0, v144
	v_exp_f32_e32 v149, v149
	v_add_f32_e32 v128, v145, v128
	v_exp_f32_e32 v150, v150
	v_add_f32_e32 v128, v146, v128
	v_exp_f32_e32 v151, v151
	v_add_f32_e32 v128, v147, v128
	v_exp_f32_e32 v152, v152
	v_add_f32_e32 v128, v148, v128
	v_exp_f32_e32 v153, v153
	v_add_f32_e32 v128, v149, v128
	v_exp_f32_e32 v154, v154
	v_add_f32_e32 v128, v150, v128
	v_exp_f32_e32 v155, v155
	v_add_f32_e32 v128, v151, v128
	v_exp_f32_e32 v156, v156
	v_add_f32_e32 v128, v152, v128
	v_exp_f32_e32 v157, v157
	v_add_f32_e32 v128, v153, v128
	v_exp_f32_e32 v158, v158
	v_add_f32_e32 v128, v154, v128
	v_exp_f32_e32 v159, v159
	v_add_f32_e32 v128, v155, v128
	v_add_f32_e32 v128, v156, v128
	v_exp_f32_e32 v195, v129
	v_add_f32_e32 v128, v157, v128
	v_exp_f32_e32 v196, v130
	v_add_f32_e32 v128, v158, v128
	v_exp_f32_e32 v197, v131
	v_add_f32_e32 v128, v159, v128
	v_exp_f32_e32 v214, v132
	v_add_f32_e32 v128, v194, v128
	v_exp_f32_e32 v215, v133
	v_add_f32_e32 v128, v195, v128
	v_exp_f32_e32 v216, v134
	v_add_f32_e32 v128, v196, v128
	v_exp_f32_e32 v217, v135
	v_add_f32_e32 v128, v197, v128
	v_exp_f32_e32 v220, v136
	v_add_f32_e32 v128, v214, v128
	v_exp_f32_e32 v221, v137
	v_add_f32_e32 v128, v215, v128
	v_exp_f32_e32 v222, v138
	v_add_f32_e32 v128, v216, v128
	v_exp_f32_e32 v228, v139
	v_add_f32_e32 v128, v217, v128
	v_exp_f32_e32 v229, v140
	v_add_f32_e32 v128, v220, v128
	v_exp_f32_e32 v230, v141
	v_add_f32_e32 v128, v221, v128
	v_exp_f32_e32 v231, v142
	v_add_f32_e32 v128, v222, v128
	v_exp_f32_e32 v143, v143
	v_add_f32_e32 v128, v228, v128
	v_add_f32_e32 v128, v229, v128
	v_add_f32_e32 v128, v230, v128
	v_add_f32_e32 v128, v231, v128
	v_add_f32_e32 v212, v143, v128
	v_mov_b32_e32 v227, v212
	v_cvt_pk_bf16_f32 v128, v144, v145
	v_cvt_pk_bf16_f32 v129, v146, v147
	v_cvt_pk_bf16_f32 v130, v148, v149
	v_cvt_pk_bf16_f32 v131, v150, v151
	v_cvt_pk_bf16_f32 v132, v152, v153
	v_cvt_pk_bf16_f32 v133, v154, v155
	v_cvt_pk_bf16_f32 v134, v156, v157
	v_cvt_pk_bf16_f32 v135, v158, v159
	v_cvt_pk_bf16_f32 v136, v194, v195
	v_cvt_pk_bf16_f32 v137, v196, v197
	v_cvt_pk_bf16_f32 v138, v214, v215
	v_cvt_pk_bf16_f32 v139, v216, v217
	v_cvt_pk_bf16_f32 v140, v220, v221
	v_cvt_pk_bf16_f32 v141, v222, v228
	v_cvt_pk_bf16_f32 v142, v229, v230
	v_cvt_pk_bf16_f32 v143, v231, v143
	s_nop 1
	v_permlane32_swap_b32_e32 v212, v227
.LBB0_359:
	s_setprio 0
	s_and_b64 vcc, exec, s[90:91]
	s_cbranch_vccnz .Lp0_bar0
	s_waitcnt vmcnt(6) lgkmcnt(0)
	s_barrier

; __device__ __forceinline__ float softmax_rel(f32x16& p0, f32x16& p1, bool first, float& m_reg, float& l_reg, bf16x8& pa0, bf16x8& pa1, bf16x8& pa2, bf16x8& pa3) {
;     ...
; #pragma unroll
;   for (int r = 0; r < 16; ++r) p0[r] = __builtin_amdgcn_exp2f(p0[r]);
; #pragma unroll
;   for (int r = 0; r < 16; ++r) p1[r] = __builtin_amdgcn_exp2f(p1[r]);
;   float ps = 0;
; #pragma unroll
;   for (int r = 0; r < 16; ++r) ps += p0[r];
; #pragma unroll
;   for (int r = 0; r < 16; ++r) ps += p1[r];
;   { auto rr = __builtin_amdgcn_permlane32_swap(__float_as_uint(ps), __float_as_uint(ps), false, false);
;     ps = __uint_as_float(rr[0]) + __uint_as_float(rr[1]); }
;   l_reg = l_reg * alpha + ps;
;   PK4(p0, 0, pa0); PK4(p0, 8, pa1); PK4(p1, 0, pa2); PK4(p1, 8, pa3);
.Lm0_exp2:
	v_exp_f32_e32 v144, v144
	v_exp_f32_e32 v145, v145
	v_exp_f32_e32 v146, v146
	v_exp_f32_e32 v147, v147
	v_exp_f32_e32 v148, v148
	v_exp_f32_e32 v194, v128
	v_add_f32_e32 v128, 0, v144
	v_exp_f32_e32 v149, v149
	v_add_f32_e32 v128, v145, v128
	v_exp_f32_e32 v150, v150
	v_add_f32_e32 v128, v146, v128
	v_exp_f32_e32 v151, v151
	v_add_f32_e32 v128, v147, v128
	v_exp_f32_e32 v152, v152
	v_add_f32_e32 v128, v148, v128
	v_exp_f32_e32 v153, v153
	v_add_f32_e32 v128, v149, v128
	v_exp_f32_e32 v154, v154
	v_add_f32_e32 v128, v150, v128
	v_exp_f32_e32 v155, v155
	v_add_f32_e32 v128, v151, v128
	v_exp_f32_e32 v156, v156
	v_add_f32_e32 v128, v152, v128
	v_exp_f32_e32 v157, v157
	v_add_f32_e32 v128, v153, v128
	v_exp_f32_e32 v158, v158
	v_add_f32_e32 v128, v154, v128
	v_exp_f32_e32 v159, v159
	v_add_f32_e32 v128, v155, v128
	v_add_f32_e32 v128, v156, v128
	v_exp_f32_e32 v195, v129
	v_add_f32_e32 v128, v157, v128
	v_exp_f32_e32 v196, v130
	v_add_f32_e32 v128, v158, v128
	v_exp_f32_e32 v197, v131
	v_add_f32_e32 v128, v159, v128
	v_exp_f32_e32 v214, v132
	v_add_f32_e32 v128, v194, v128
	v_exp_f32_e32 v215, v133
	v_add_f32_e32 v128, v195, v128
	v_exp_f32_e32 v216, v134
	v_add_f32_e32 v128, v196, v128
	v_exp_f32_e32 v217, v135
	v_add_f32_e32 v128, v197, v128
	v_exp_f32_e32 v220, v136
	v_add_f32_e32 v128, v214, v128
	v_exp_f32_e32 v221, v137
	v_add_f32_e32 v128, v215, v128
	v_exp_f32_e32 v222, v138
	v_add_f32_e32 v128, v216, v128
	v_exp_f32_e32 v228, v139
	v_add_f32_e32 v128, v217, v128
	v_exp_f32_e32 v229, v140
	v_add_f32_e32 v128, v220, v128
	v_exp_f32_e32 v230, v141
	v_add_f32_e32 v128, v221, v128
	v_exp_f32_e32 v231, v142
	v_add_f32_e32 v128, v222, v128
	v_exp_f32_e32 v143, v143
	v_add_f32_e32 v128, v228, v128
	v_add_f32_e32 v128, v229, v128
	v_add_f32_e32 v128, v230, v128
	v_add_f32_e32 v128, v231, v128
	v_add_f32_e32 v212, v143, v128
	v_mov_b32_e32 v227, v212
	v_cvt_pk_bf16_f32 v128, v144, v145
	v_cvt_pk_bf16_f32 v129, v146, v147
	v_cvt_pk_bf16_f32 v130, v148, v149
	v_cvt_pk_bf16_f32 v131, v150, v151
	v_cvt_pk_bf16_f32 v132, v152, v153
	v_cvt_pk_bf16_f32 v133, v154, v155
	v_cvt_pk_bf16_f32 v134, v156, v157
	v_cvt_pk_bf16_f32 v135, v158, v159
	v_cvt_pk_bf16_f32 v136, v194, v195
	v_cvt_pk_bf16_f32 v137, v196, v197
	v_cvt_pk_bf16_f32 v138, v214, v215
	v_cvt_pk_bf16_f32 v139, v216, v217
	v_cvt_pk_bf16_f32 v140, v220, v221
	v_cvt_pk_bf16_f32 v141, v222, v228
	v_cvt_pk_bf16_f32 v142, v229, v230
	v_cvt_pk_bf16_f32 v143, v231, v143
	s_nop 1
	v_permlane32_swap_b32_e32 v212, v227
	v_cmp_gt_f32_e32 vcc, 1.0, v226
	s_cbranch_vccnz .Lm0_resc
	s_branch .LBB0_359

; __device__ __forceinline__ float softmax_rel(f32x16& p0, f32x16& p1, bool first, float& m_reg, float& l_reg, bf16x8& pa0, bf16x8& pa1, bf16x8& pa2, bf16x8& pa3) {
;     ...
; #pragma unroll
;   for (int r = 0; r < 16; ++r) p0[r] = __builtin_amdgcn_exp2f(p0[r]);
; #pragma unroll
;   for (int r = 0; r < 16; ++r) p1[r] = __builtin_amdgcn_exp2f(p1[r]);
;   float ps = 0;
; #pragma unroll
;   for (int r = 0; r < 16; ++r) ps += p0[r];
; #pragma unroll
;   for (int r = 0; r < 16; ++r) ps += p1[r];
;   { auto rr = __builtin_amdgcn_permlane32_swap(__float_as_uint(ps), __float_as_uint(ps), false, false);
;     ps = __uint_as_float(rr[0]) + __uint_as_float(rr[1]); }
;   l_reg = l_reg * alpha + ps;
;   PK4(p0, 0, pa0); PK4(p0, 8, pa1); PK4(p1, 0, pa2); PK4(p1, 8, pa3);
.LBB0_388:
	v_exp_f32_e32 v144, v144
	v_exp_f32_e32 v145, v145
	v_exp_f32_e32 v146, v146
	v_exp_f32_e32 v147, v147
	v_exp_f32_e32 v148, v148
	v_exp_f32_e32 v194, v128
	v_add_f32_e32 v128, 0, v144
	v_exp_f32_e32 v149, v149
	v_add_f32_e32 v128, v145, v128
	v_exp_f32_e32 v150, v150
	v_add_f32_e32 v128, v146, v128
	v_exp_f32_e32 v151, v151
	v_add_f32_e32 v128, v147, v128
	v_exp_f32_e32 v152, v152
	v_add_f32_e32 v128, v148, v128
	v_exp_f32_e32 v153, v153
	v_add_f32_e32 v128, v149, v128
	v_exp_f32_e32 v154, v154
	v_add_f32_e32 v128, v150, v128
	v_exp_f32_e32 v155, v155
	v_add_f32_e32 v128, v151, v128
	v_exp_f32_e32 v156, v156
	v_add_f32_e32 v128, v152, v128
	v_exp_f32_e32 v157, v157
	v_add_f32_e32 v128, v153, v128
	v_exp_f32_e32 v158, v158
	v_add_f32_e32 v128, v154, v128
	v_exp_f32_e32 v159, v159
	v_add_f32_e32 v128, v155, v128
	v_add_f32_e32 v128, v156, v128
	v_exp_f32_e32 v195, v129
	v_add_f32_e32 v128, v157, v128
	v_exp_f32_e32 v196, v130
	v_add_f32_e32 v128, v158, v128
	v_exp_f32_e32 v197, v131
	v_add_f32_e32 v128, v159, v128
	v_exp_f32_e32 v214, v132
	v_add_f32_e32 v128, v194, v128
	v_exp_f32_e32 v215, v133
	v_add_f32_e32 v128, v195, v128
	v_exp_f32_e32 v216, v134
	v_add_f32_e32 v128, v196, v128
	v_exp_f32_e32 v217, v135
	v_add_f32_e32 v128, v197, v128
	v_exp_f32_e32 v220, v136
	v_add_f32_e32 v128, v214, v128
	v_exp_f32_e32 v221, v137
	v_add_f32_e32 v128, v215, v128
	v_exp_f32_e32 v222, v138
	v_add_f32_e32 v128, v216, v128
	v_exp_f32_e32 v223, v139
	v_add_f32_e32 v128, v217, v128
	v_exp_f32_e32 v231, v140
	v_add_f32_e32 v128, v220, v128
	v_exp_f32_e32 v232, v141
	v_add_f32_e32 v128, v221, v128
	v_exp_f32_e32 v233, v142
	v_add_f32_e32 v128, v222, v128
	v_exp_f32_e32 v143, v143
	v_add_f32_e32 v128, v223, v128
	v_add_f32_e32 v128, v231, v128
	v_add_f32_e32 v128, v232, v128
	v_add_f32_e32 v128, v233, v128
	v_add_f32_e32 v212, v143, v128
	v_mov_b32_e32 v230, v212
	v_cvt_pk_bf16_f32 v128, v144, v145
	v_cvt_pk_bf16_f32 v129, v146, v147
	v_cvt_pk_bf16_f32 v130, v148, v149
	v_cvt_pk_bf16_f32 v131, v150, v151
	v_cvt_pk_bf16_f32 v132, v152, v153
	v_cvt_pk_bf16_f32 v133, v154, v155
	v_cvt_pk_bf16_f32 v134, v156, v157
	v_cvt_pk_bf16_f32 v135, v158, v159
	v_cvt_pk_bf16_f32 v136, v194, v195
	v_cvt_pk_bf16_f32 v137, v196, v197
	v_cvt_pk_bf16_f32 v138, v214, v215
	v_cvt_pk_bf16_f32 v139, v216, v217
	v_cvt_pk_bf16_f32 v140, v220, v221
	v_cvt_pk_bf16_f32 v141, v222, v223
	v_cvt_pk_bf16_f32 v142, v231, v232
	v_cvt_pk_bf16_f32 v143, v233, v143
	s_nop 1
	v_permlane32_swap_b32_e32 v212, v230
.LBB0_392:
	s_setprio 0
	s_and_b64 vcc, exec, s[50:51]
	s_cbranch_vccnz .Lp1_bar0
	s_waitcnt vmcnt(6) lgkmcnt(0)
	s_barrier

; __device__ __forceinline__ float softmax_rel(f32x16& p0, f32x16& p1, bool first, float& m_reg, float& l_reg, bf16x8& pa0, bf16x8& pa1, bf16x8& pa2, bf16x8& pa3) {
;     ...
; #pragma unroll
;   for (int r = 0; r < 16; ++r) p0[r] = __builtin_amdgcn_exp2f(p0[r]);
; #pragma unroll
;   for (int r = 0; r < 16; ++r) p1[r] = __builtin_amdgcn_exp2f(p1[r]);
;   float ps = 0;
; #pragma unroll
;   for (int r = 0; r < 16; ++r) ps += p0[r];
; #pragma unroll
;   for (int r = 0; r < 16; ++r) ps += p1[r];
;   { auto rr = __builtin_amdgcn_permlane32_swap(__float_as_uint(ps), __float_as_uint(ps), false, false);
;     ps = __uint_as_float(rr[0]) + __uint_as_float(rr[1]); }
;   l_reg = l_reg * alpha + ps;
;   PK4(p0, 0, pa0); PK4(p0, 8, pa1); PK4(p1, 0, pa2); PK4(p1, 8, pa3);
.Lm1_exp2:
	v_exp_f32_e32 v144, v144
	v_exp_f32_e32 v145, v145
	v_exp_f32_e32 v146, v146
	v_exp_f32_e32 v147, v147
	v_exp_f32_e32 v148, v148
	v_exp_f32_e32 v194, v128
	v_add_f32_e32 v128, 0, v144
	v_exp_f32_e32 v149, v149
	v_add_f32_e32 v128, v145, v128
	v_exp_f32_e32 v150, v150
	v_add_f32_e32 v128, v146, v128
	v_exp_f32_e32 v151, v151
	v_add_f32_e32 v128, v147, v128
	v_exp_f32_e32 v152, v152
	v_add_f32_e32 v128, v148, v128
	v_exp_f32_e32 v153, v153
	v_add_f32_e32 v128, v149, v128
	v_exp_f32_e32 v154, v154
	v_add_f32_e32 v128, v150, v128
	v_exp_f32_e32 v155, v155
	v_add_f32_e32 v128, v151, v128
	v_exp_f32_e32 v156, v156
	v_add_f32_e32 v128, v152, v128
	v_exp_f32_e32 v157, v157
	v_add_f32_e32 v128, v153, v128
	v_exp_f32_e32 v158, v158
	v_add_f32_e32 v128, v154, v128
	v_exp_f32_e32 v159, v159
	v_add_f32_e32 v128, v155, v128
	v_add_f32_e32 v128, v156, v128
	v_exp_f32_e32 v195, v129
	v_add_f32_e32 v128, v157, v128
	v_exp_f32_e32 v196, v130
	v_add_f32_e32 v128, v158, v128
	v_exp_f32_e32 v197, v131
	v_add_f32_e32 v128, v159, v128
	v_exp_f32_e32 v214, v132
	v_add_f32_e32 v128, v194, v128
	v_exp_f32_e32 v215, v133
	v_add_f32_e32 v128, v195, v128
	v_exp_f32_e32 v216, v134
	v_add_f32_e32 v128, v196, v128
	v_exp_f32_e32 v217, v135
	v_add_f32_e32 v128, v197, v128
	v_exp_f32_e32 v220, v136
	v_add_f32_e32 v128, v214, v128
	v_exp_f32_e32 v221, v137
	v_add_f32_e32 v128, v215, v128
	v_exp_f32_e32 v222, v138
	v_add_f32_e32 v128, v216, v128
	v_exp_f32_e32 v223, v139
	v_add_f32_e32 v128, v217, v128
	v_exp_f32_e32 v231, v140
	v_add_f32_e32 v128, v220, v128
	v_exp_f32_e32 v232, v141
	v_add_f32_e32 v128, v221, v128
	v_exp_f32_e32 v233, v142
	v_add_f32_e32 v128, v222, v128
	v_exp_f32_e32 v143, v143
	v_add_f32_e32 v128, v223, v128
	v_add_f32_e32 v128, v231, v128
	v_add_f32_e32 v128, v232, v128
	v_add_f32_e32 v128, v233, v128
	v_add_f32_e32 v212, v143, v128
	v_mov_b32_e32 v230, v212
	v_cvt_pk_bf16_f32 v128, v144, v145
	v_cvt_pk_bf16_f32 v129, v146, v147
	v_cvt_pk_bf16_f32 v130, v148, v149
	v_cvt_pk_bf16_f32 v131, v150, v151
	v_cvt_pk_bf16_f32 v132, v152, v153
	v_cvt_pk_bf16_f32 v133, v154, v155
	v_cvt_pk_bf16_f32 v134, v156, v157
	v_cvt_pk_bf16_f32 v135, v158, v159
	v_cvt_pk_bf16_f32 v136, v194, v195
	v_cvt_pk_bf16_f32 v137, v196, v197
	v_cvt_pk_bf16_f32 v138, v214, v215
	v_cvt_pk_bf16_f32 v139, v216, v217
	v_cvt_pk_bf16_f32 v140, v220, v221
	v_cvt_pk_bf16_f32 v141, v222, v223
	v_cvt_pk_bf16_f32 v142, v231, v232
	v_cvt_pk_bf16_f32 v143, v233, v143
	s_nop 1
	v_permlane32_swap_b32_e32 v212, v230
	v_cmp_gt_f32_e32 vcc, 1.0, v229
	s_cbranch_vccnz .Lm1_resc
	s_branch .LBB0_392
